# prologue c_cat table copy: 16 loads in flight per pass instead of one round trip per element pair
# speedup vs baseline: 1.0118x; 1.0054x over previous
; DI void prologue_phase(const int tid, LAS unsigned char* lds, const P& p, int G, int c) {
;     ...
;         for (int idx = tid; idx < 16 * 16 * 128; idx += 512) { const int k = idx & 127, gh = idx >> 7;
;             ccat[idx] = f2bf(k < 64 ? p.in[8][gh * 64 + k] : p.in[9][gh * 64 + k - 64]); }
.LBB0_1638:
	s_or_b64 exec, exec, s[8:9]
	s_mov_b32 s0, 0x8000
	v_cmp_gt_i32_e32 vcc, s0, v182
	s_and_saveexec_b64 s[6:7], vcc
	s_cbranch_execz .LBB0_1650
	v_and_b32_e32 v0, 0x7f, v182
	v_lshrrev_b32_e32 v1, 7, v182
	v_and_b32_e32 v2, 63, v0
	v_lshl_or_b32 v10, v1, 6, v2
	v_mov_b32_e32 v11, 0
	v_readlane_b32 s72, v253, 52
	v_readlane_b32 s73, v253, 53
	v_readlane_b32 s74, v253, 54
	v_readlane_b32 s75, v253, 55
	v_cmp_gt_u32_e32 vcc, 64, v0
	v_mov_b32_e32 v2, s74
	v_mov_b32_e32 v3, s75
	v_mov_b32_e32 v4, s72
	v_mov_b32_e32 v5, s73
	v_cndmask_b32_e32 v2, v2, v4, vcc
	v_cndmask_b32_e32 v3, v3, v5, vcc
	v_mov_b32_e32 v12, v182
	v_mov_b32_e32 v13, 0
	s_mov_b64 s[0:1], 0x1000
	s_mov_b64 s[4:5], 0x4000
	v_lshl_add_u64 v[16:17], v[10:11], 2, v[2:3]
	v_lshl_add_u64 v[24:25], v[12:13], 1, s[42:43]
	v_lshl_add_u64 v[18:19], v[16:17], 0, s[0:1]
	v_lshl_add_u64 v[26:27], v[24:25], 0, s[0:1]
	v_lshl_add_u64 v[20:21], v[18:19], 0, s[0:1]
	v_lshl_add_u64 v[28:29], v[26:27], 0, s[0:1]
	v_lshl_add_u64 v[22:23], v[20:21], 0, s[0:1]
	v_lshl_add_u64 v[30:31], v[28:29], 0, s[0:1]
	s_mov_b32 s8, 4
.Lccat_pass:
	global_load_dword v44, v[16:17], off
	global_load_dword v45, v[16:17], off offset:1024
	global_load_dword v46, v[16:17], off offset:2048
	global_load_dword v47, v[16:17], off offset:3072
	global_load_dword v48, v[18:19], off
	global_load_dword v49, v[18:19], off offset:1024
	global_load_dword v50, v[18:19], off offset:2048
	global_load_dword v51, v[18:19], off offset:3072
	global_load_dword v52, v[20:21], off
	global_load_dword v53, v[20:21], off offset:1024
	global_load_dword v54, v[20:21], off offset:2048
	global_load_dword v55, v[20:21], off offset:3072
	global_load_dword v56, v[22:23], off
	global_load_dword v57, v[22:23], off offset:1024
	global_load_dword v58, v[22:23], off offset:2048
	global_load_dword v59, v[22:23], off offset:3072
	v_lshl_add_u64 v[16:17], v[16:17], 0, s[4:5]
	v_lshl_add_u64 v[18:19], v[18:19], 0, s[4:5]
	v_lshl_add_u64 v[20:21], v[20:21], 0, s[4:5]
	v_lshl_add_u64 v[22:23], v[22:23], 0, s[4:5]
	s_waitcnt vmcnt(0)
	v_cvt_pk_bf16_f32 v60, v44, v45
	v_cvt_pk_bf16_f32 v61, v46, v47
	v_cvt_pk_bf16_f32 v62, v48, v49
	v_cvt_pk_bf16_f32 v63, v50, v51
	v_cvt_pk_bf16_f32 v64, v52, v53
	v_cvt_pk_bf16_f32 v65, v54, v55
	v_cvt_pk_bf16_f32 v66, v56, v57
	v_cvt_pk_bf16_f32 v67, v58, v59
	global_store_short v[24:25], v60, off
	global_store_short_d16_hi v[24:25], v60, off offset:1024
	global_store_short v[24:25], v61, off offset:2048
	global_store_short_d16_hi v[24:25], v61, off offset:3072
	global_store_short v[26:27], v62, off
	global_store_short_d16_hi v[26:27], v62, off offset:1024
	global_store_short v[26:27], v63, off offset:2048
	global_store_short_d16_hi v[26:27], v63, off offset:3072
	global_store_short v[28:29], v64, off
	global_store_short_d16_hi v[28:29], v64, off offset:1024
	global_store_short v[28:29], v65, off offset:2048
	global_store_short_d16_hi v[28:29], v65, off offset:3072
	global_store_short v[30:31], v66, off
	global_store_short_d16_hi v[30:31], v66, off offset:1024
	global_store_short v[30:31], v67, off offset:2048
	global_store_short_d16_hi v[30:31], v67, off offset:3072
	v_lshl_add_u64 v[24:25], v[24:25], 0, s[4:5]
	v_lshl_add_u64 v[26:27], v[26:27], 0, s[4:5]
	v_lshl_add_u64 v[28:29], v[28:29], 0, s[4:5]
	v_lshl_add_u64 v[30:31], v[30:31], 0, s[4:5]
	s_add_i32 s8, s8, -1
	s_cmp_lg_u32 s8, 0
	s_cbranch_scc1 .Lccat_pass
